# grid barrier: arrival atomic issued before the LDS read of the counts; two polls in flight per waiter
# baseline (speedup 1.0000x reference)
.Lxb0_top:
	ds_read_b32 v242, v241
	v_lshlrev_b32_e64 v245, 8, s31
	v_mov_b32_e32 v247, 1
	v_add_u32_e32 v246, 0x1400, v245
	s_waitcnt lgkmcnt(0)
	v_cmp_ne_u32_e32 vcc, 0, v242
	s_cbranch_vccz .Lxb0_census
	global_atomic_add v248, v246, v247, s[60:61] sc0
	ds_read_b96 v[242:244], v241
	v_add_u32_e32 v253, 0x2400, v245
	v_mov_b32_e32 v252, 0
	s_waitcnt lgkmcnt(0)
	v_add_u32_e32 v249, 1, v244
	ds_write_b32 v241, v249 offset:8
	v_mul_lo_u32 v250, v249, v242
	v_mul_lo_u32 v251, v249, v243
	s_waitcnt vmcnt(0)
	buffer_inv sc1
	v_add_u32_e32 v248, 1, v248
	v_cmp_eq_u32_e32 vcc, v248, v250
	s_cbranch_vccz .Lxb0_wait
	buffer_wbl2 sc1
	s_waitcnt vmcnt(0)
	v_mov_b32_e32 v246, 0x3400
	global_atomic_add v248, v246, v247, s[60:61] sc0
	s_waitcnt vmcnt(0)
	v_add_u32_e32 v248, 1, v248
	v_cmp_ge_u32_e32 vcc, v248, v251
	s_cbranch_vccnz .Lxb0_rel
	global_load_dword v248, v246, s[60:61] sc1
	s_sleep 2
	global_load_dword v254, v246, s[60:61] sc1
.Lxb0_tloop:
	s_waitcnt vmcnt(1)
	v_cmp_ge_u32_e32 vcc, v248, v251
	s_cbranch_vccnz .Lxb0_rel
	global_load_dword v248, v246, s[60:61] sc1
	s_waitcnt vmcnt(1)
	v_cmp_ge_u32_e32 vcc, v254, v251
	s_cbranch_vccnz .Lxb0_rel
	global_load_dword v254, v246, s[60:61] sc1
	v_add_u32_e32 v252, 1, v252
	v_cmp_gt_u32_e32 vcc, 0x100000, v252
	s_cbranch_vccnz .Lxb0_tloop

.Lxb0_wait:
	global_load_dword v248, v253, s[60:61] sc1
	s_sleep 2
	global_load_dword v254, v253, s[60:61] sc1
.Lxb0_wloop:
	s_waitcnt vmcnt(1)
	v_cmp_ge_u32_e32 vcc, v248, v249
	s_cbranch_vccnz .Lxb0_wdone
	global_load_dword v248, v253, s[60:61] sc1
	s_waitcnt vmcnt(1)
	v_cmp_ge_u32_e32 vcc, v254, v249
	s_cbranch_vccnz .Lxb0_wdone
	global_load_dword v254, v253, s[60:61] sc1
	v_add_u32_e32 v252, 1, v252
	v_cmp_gt_u32_e32 vcc, 0x100000, v252
	s_cbranch_vccnz .Lxb0_wloop

.Lxb2_top:
	ds_read_b32 v242, v241
	v_lshlrev_b32_e64 v245, 8, s31
	v_mov_b32_e32 v247, 1
	v_add_u32_e32 v246, 0x1400, v245
	s_waitcnt lgkmcnt(0)
	v_cmp_ne_u32_e32 vcc, 0, v242
	s_cbranch_vccz .Lxb2_census
	global_atomic_add v248, v246, v247, s[60:61] sc0
	ds_read_b96 v[242:244], v241
	v_add_u32_e32 v253, 0x2400, v245
	v_mov_b32_e32 v252, 0
	s_waitcnt lgkmcnt(0)
	v_add_u32_e32 v249, 1, v244
	ds_write_b32 v241, v249 offset:8
	v_mul_lo_u32 v250, v249, v242
	v_mul_lo_u32 v251, v249, v243
	s_waitcnt vmcnt(0)
	buffer_inv sc1
	v_add_u32_e32 v248, 1, v248
	v_cmp_eq_u32_e32 vcc, v248, v250
	s_cbranch_vccz .Lxb2_wait
	s_waitcnt vmcnt(0)
	v_mov_b32_e32 v246, 0x3400
	global_atomic_add v248, v246, v247, s[60:61] sc0
	s_waitcnt vmcnt(0)
	v_add_u32_e32 v248, 1, v248
	v_cmp_ge_u32_e32 vcc, v248, v251
	s_cbranch_vccnz .Lxb2_rel
	global_load_dword v248, v246, s[60:61] sc1
	s_sleep 2
	global_load_dword v254, v246, s[60:61] sc1
